# P9 epilogue: nt (streaming) hint on the final-use per-token x / ple row loads so they do not displace fp6 table rows in L2
# baseline (speedup 1.0000x reference)
.LpB_epi:
	ds_write_b32 v137, v178
	ds_write_b32 v183, v179
	ds_write_b32 v184, v176
	ds_write_b32 v185, v177
	ds_write_b32 v186, v174
	ds_write_b32 v187, v175
	ds_write_b32 v188, v172
	ds_write_b32 v189, v173
	ds_write_b32 v190, v170
	ds_write_b32 v191, v171
	ds_write_b32 v192, v168
	ds_write_b32 v193, v169
	ds_write_b32 v194, v166
	ds_write_b32 v195, v167
	ds_write_b32 v196, v180
	ds_write_b32 v197, v181
	v_lshl_add_u64 v[18:19], v[146:147], 0, v[164:165]
	global_load_dwordx4 v[2:5], v[18:19], off nt
	global_load_dwordx4 v[6:9], v[162:163], off nt
	global_load_dwordx4 v[10:13], v[18:19], off offset:16 nt
	global_load_dwordx4 v[14:17], v[162:163], off offset:16 nt
	ds_read_b128 v[18:21], v201
	ds_read_b128 v[22:25], v201 offset:16
	ds_read_b128 v[26:29], v201 offset:32
	ds_read_b128 v[30:33], v201 offset:48
	s_waitcnt vmcnt(3)
	v_lshlrev_b32_e32 v34, 16, v2
	s_waitcnt vmcnt(2)
	v_lshlrev_b32_e32 v36, 16, v6
	v_and_b32_e32 v37, 0xffff0000, v6
	v_lshlrev_b32_e32 v6, 16, v7
	v_and_b32_e32 v7, 0xffff0000, v7
	v_lshlrev_b32_e32 v40, 16, v8
	v_and_b32_e32 v41, 0xffff0000, v8
	v_lshlrev_b32_e32 v8, 16, v9
	v_and_b32_e32 v9, 0xffff0000, v9
	v_and_b32_e32 v35, 0xffff0000, v2
	v_lshlrev_b32_e32 v2, 16, v3
	v_and_b32_e32 v3, 0xffff0000, v3
	v_lshlrev_b32_e32 v38, 16, v4
	v_and_b32_e32 v39, 0xffff0000, v4
	v_lshlrev_b32_e32 v4, 16, v5
	v_and_b32_e32 v5, 0xffff0000, v5
	s_waitcnt vmcnt(0)
	v_lshlrev_b32_e32 v44, 16, v14
	v_and_b32_e32 v45, 0xffff0000, v14
	v_lshlrev_b32_e32 v14, 16, v15
	v_and_b32_e32 v15, 0xffff0000, v15
	s_waitcnt lgkmcnt(3)
	v_pk_fma_f32 v[18:19], v[36:37], s[12:13], v[18:19] op_sel_hi:[1,0,1]
	v_pk_fma_f32 v[6:7], v[6:7], s[12:13], v[20:21] op_sel_hi:[1,0,1]
	s_waitcnt lgkmcnt(2)
	v_pk_fma_f32 v[20:21], v[40:41], s[12:13], v[22:23] op_sel_hi:[1,0,1]
	v_pk_fma_f32 v[8:9], v[8:9], s[12:13], v[24:25] op_sel_hi:[1,0,1]
	s_waitcnt lgkmcnt(1)
	v_pk_fma_f32 v[22:23], v[44:45], s[12:13], v[26:27] op_sel_hi:[1,0,1]
	v_pk_fma_f32 v[14:15], v[14:15], s[12:13], v[28:29] op_sel_hi:[1,0,1]
	v_pk_add_f32 v[18:19], v[18:19], v[34:35]
	v_pk_add_f32 v[26:27], v[6:7], v[2:3]
	v_pk_add_f32 v[20:21], v[20:21], v[38:39]
	v_pk_add_f32 v[28:29], v[8:9], v[4:5]
	v_lshlrev_b32_e32 v42, 16, v10
	v_and_b32_e32 v43, 0xffff0000, v10
	v_lshlrev_b32_e32 v10, 16, v11
	v_and_b32_e32 v11, 0xffff0000, v11
	v_lshlrev_b32_e32 v48, 16, v16
	v_and_b32_e32 v49, 0xffff0000, v16
	v_lshlrev_b32_e32 v16, 16, v17
	v_and_b32_e32 v17, 0xffff0000, v17
	v_mov_b32_e32 v2, v18
	v_mov_b32_e32 v3, v27
	v_pk_mov_b32 v[4:5], v[18:19], v[26:27] op_sel:[1,0]
	v_mov_b32_e32 v6, v20
	v_mov_b32_e32 v7, v29
	v_pk_mov_b32 v[8:9], v[20:21], v[28:29] op_sel:[1,0]
	v_lshlrev_b32_e32 v46, 16, v12
	v_and_b32_e32 v47, 0xffff0000, v12
	v_lshlrev_b32_e32 v12, 16, v13
	v_and_b32_e32 v13, 0xffff0000, v13
	s_waitcnt lgkmcnt(0)
	v_pk_fma_f32 v[24:25], v[48:49], s[12:13], v[30:31] op_sel_hi:[1,0,1]
	v_pk_fma_f32 v[16:17], v[16:17], s[12:13], v[32:33] op_sel_hi:[1,0,1]
	v_pk_add_f32 v[22:23], v[22:23], v[42:43]
	v_pk_add_f32 v[10:11], v[14:15], v[10:11]
	v_pk_add_f32 v[2:3], v[2:3], v[4:5]
	v_pk_add_f32 v[4:5], v[6:7], v[8:9]
	v_pk_add_f32 v[14:15], v[24:25], v[46:47]
	v_pk_add_f32 v[12:13], v[16:17], v[12:13]
	v_pk_add_f32 v[16:17], v[22:23], v[22:23] op_sel:[0,1] op_sel_hi:[1,0]
	v_pk_add_f32 v[24:25], v[10:11], v[10:11] op_sel:[1,0] op_sel_hi:[0,1]
	v_add_f32_e32 v6, v2, v3
	v_pk_add_f32 v[2:3], v[4:5], v[4:5] op_sel:[0,1] op_sel_hi:[1,0]
	v_mov_b32_e32 v31, v14
	v_add_f32_e32 v30, 0, v6
	v_mov_b32_e32 v3, v15
	v_mov_b32_e32 v17, v13
	v_mov_b32_e32 v25, v12
	v_pk_add_f32 v[2:3], v[30:31], v[2:3]
	v_pk_add_f32 v[4:5], v[16:17], v[24:25]
	s_nop 0
	v_pk_add_f32 v[2:3], v[2:3], v[4:5]
	s_nop 0
	v_add_f32_e32 v2, v2, v3
	s_nop 1
	v_add_f32_dpp v2, v2, v2 quad_perm:[1,0,3,2] row_mask:0xf bank_mask:0xf bound_ctrl:1
	s_nop 1
	v_add_f32_dpp v2, v2, v2 quad_perm:[2,3,0,1] row_mask:0xf bank_mask:0xf bound_ctrl:1
	s_nop 1
	v_add_f32_dpp v2, v2, v2 row_half_mirror row_mask:0xf bank_mask:0xf bound_ctrl:1
	s_nop 1
	v_add_f32_dpp v2, v2, v2 row_mirror row_mask:0xf bank_mask:0xf bound_ctrl:1
	s_nop 1
	v_add_f32_dpp v2, v2, v2 row_bcast:15 row_mask:0xa bank_mask:0xf
	s_nop 1
	v_add_f32_dpp v2, v2, v2 row_bcast:31 row_mask:0xc bank_mask:0xf
	s_nop 1
	v_readlane_b32 s53, v2, 63
	global_load_dwordx4 v[2:5], v[156:157], off
	global_load_dwordx4 v[6:9], v[158:159], off
	v_mov_b32_e32 v16, s53
	v_mul_f32_e32 v16, 0x3a800000, v16
	v_pk_add_f32 v[18:19], v[18:19], v[16:17] op_sel_hi:[1,0] neg_lo:[0,1] neg_hi:[0,1]
	v_pk_add_f32 v[24:25], v[26:27], v[16:17] op_sel_hi:[1,0] neg_lo:[0,1] neg_hi:[0,1]
	v_pk_add_f32 v[20:21], v[20:21], v[16:17] op_sel_hi:[1,0] neg_lo:[0,1] neg_hi:[0,1]
	v_pk_add_f32 v[26:27], v[28:29], v[16:17] op_sel_hi:[1,0] neg_lo:[0,1] neg_hi:[0,1]
	v_pk_add_f32 v[22:23], v[22:23], v[16:17] op_sel_hi:[1,0] neg_lo:[0,1] neg_hi:[0,1]
	v_pk_add_f32 v[10:11], v[10:11], v[16:17] op_sel_hi:[1,0] neg_lo:[0,1] neg_hi:[0,1]
	v_pk_add_f32 v[14:15], v[14:15], v[16:17] op_sel_hi:[1,0] neg_lo:[0,1] neg_hi:[0,1]
	v_pk_add_f32 v[12:13], v[12:13], v[16:17] op_sel_hi:[1,0] neg_lo:[0,1] neg_hi:[0,1]
	v_pk_mul_f32 v[16:17], v[18:19], v[18:19]
	v_pk_mul_f32 v[28:29], v[24:25], v[24:25]
	v_add_f32_e32 v16, v16, v17
	v_add_f32_e32 v16, v28, v16
	v_pk_mul_f32 v[30:31], v[20:21], v[20:21]
	v_add_f32_e32 v16, v29, v16
	v_add_f32_e32 v16, v30, v16
	v_pk_mul_f32 v[32:33], v[26:27], v[26:27]
	v_add_f32_e32 v16, v31, v16
	v_add_f32_e32 v16, v32, v16
	v_pk_mul_f32 v[34:35], v[22:23], v[22:23]
	v_add_f32_e32 v16, v33, v16
	v_add_f32_e32 v16, v34, v16
	v_pk_mul_f32 v[36:37], v[10:11], v[10:11]
	v_add_f32_e32 v16, v35, v16
	v_add_f32_e32 v16, v36, v16
	v_pk_mul_f32 v[38:39], v[14:15], v[14:15]
	v_add_f32_e32 v16, v37, v16
	v_add_f32_e32 v16, v38, v16
	v_pk_mul_f32 v[40:41], v[12:13], v[12:13]
	v_add_f32_e32 v16, v39, v16
	v_add_f32_e32 v16, v40, v16
	v_add_f32_e32 v16, v41, v16
	s_nop 1
	v_add_f32_dpp v16, v16, v16 quad_perm:[1,0,3,2] row_mask:0xf bank_mask:0xf bound_ctrl:1
	s_nop 1
	v_add_f32_dpp v16, v16, v16 quad_perm:[2,3,0,1] row_mask:0xf bank_mask:0xf bound_ctrl:1
	s_nop 1
	v_add_f32_dpp v16, v16, v16 row_half_mirror row_mask:0xf bank_mask:0xf bound_ctrl:1
	s_nop 1
	v_add_f32_dpp v16, v16, v16 row_mirror row_mask:0xf bank_mask:0xf bound_ctrl:1
	s_nop 1
	v_add_f32_dpp v16, v16, v16 row_bcast:15 row_mask:0xa bank_mask:0xf
	s_nop 1
	v_add_f32_dpp v16, v16, v16 row_bcast:31 row_mask:0xc bank_mask:0xf
	s_nop 1
	v_readlane_b32 s53, v16, 63
	s_nop 3
	v_mov_b32_e32 v16, s53
	v_fmamk_f32 v16, v16, 0x3a800000, v149
	v_mul_f32_e32 v17, 0x4b800000, v16
	v_cmp_gt_f32_e64 s[2:3], s30, v16
	s_nop 1
	v_cndmask_b32_e64 v16, v16, v17, s[2:3]
	v_rsq_f32_e32 v28, v16
	v_lshlrev_b64 v[16:17], 12, v[142:143]
	v_lshl_add_u64 v[16:17], v[160:161], 0, v[16:17]
	v_add_u32_e32 v142, s6, v142
	v_mul_f32_e32 v29, 0x45800000, v28
	v_cndmask_b32_e64 v28, v28, v29, s[2:3]
	v_pk_mul_f32 v[18:19], v[18:19], v[28:29] op_sel_hi:[1,0]
	v_pk_mul_f32 v[24:25], v[24:25], v[28:29] op_sel_hi:[1,0]
	s_waitcnt vmcnt(0)
	v_pk_fma_f32 v[2:3], v[2:3], v[18:19], v[6:7]
	v_pk_fma_f32 v[4:5], v[4:5], v[24:25], v[8:9]
	global_store_dwordx4 v[16:17], v[2:5], off
	global_load_dwordx4 v[2:5], v[156:157], off offset:16
	s_nop 0
	global_load_dwordx4 v[6:9], v[158:159], off offset:16
	v_pk_mul_f32 v[18:19], v[20:21], v[28:29] op_sel_hi:[1,0]
	v_pk_mul_f32 v[20:21], v[26:27], v[28:29] op_sel_hi:[1,0]
	v_pk_mul_f32 v[10:11], v[10:11], v[28:29] op_sel_hi:[1,0]
	v_cmp_lt_i32_e64 s[2:3], s31, v142
	v_pk_mul_f32 v[12:13], v[12:13], v[28:29] op_sel_hi:[1,0]
	s_or_b64 s[10:11], s[2:3], s[10:11]
	s_waitcnt vmcnt(0)
	v_pk_fma_f32 v[2:3], v[2:3], v[18:19], v[6:7]
	v_pk_fma_f32 v[4:5], v[4:5], v[20:21], v[8:9]
	global_store_dwordx4 v[16:17], v[2:5], off offset:16
	global_load_dwordx4 v[2:5], v[156:157], off offset:32
	s_nop 0
	global_load_dwordx4 v[6:9], v[158:159], off offset:32
	v_pk_mul_f32 v[18:19], v[22:23], v[28:29] op_sel_hi:[1,0]
	s_waitcnt vmcnt(0)
	v_pk_fma_f32 v[4:5], v[4:5], v[10:11], v[8:9]
	v_pk_fma_f32 v[2:3], v[2:3], v[18:19], v[6:7]
	global_store_dwordx4 v[16:17], v[2:5], off offset:32
	global_load_dwordx4 v[2:5], v[156:157], off offset:48
	s_nop 0
	global_load_dwordx4 v[6:9], v[158:159], off offset:48
	v_pk_mul_f32 v[10:11], v[14:15], v[28:29] op_sel_hi:[1,0]
	s_waitcnt vmcnt(0)
	v_pk_fma_f32 v[4:5], v[12:13], v[4:5], v[8:9]
	v_pk_fma_f32 v[2:3], v[10:11], v[2:3], v[6:7]
	global_store_dwordx4 v[16:17], v[2:5], off offset:48
	s_andn2_b64 exec, exec, s[10:11]
	s_cbranch_execz .LBB0_3658

.LBB0_3669:
	s_andn2_saveexec_b64 s[14:15], s[2:3]
	s_cbranch_execz .LBB0_3660
	v_lshl_add_u64 v[40:41], v[140:141], 0, s[12:13]
	ds_read_b128 v[0:3], v169 offset:8192
	ds_read_b128 v[4:7], v169
	ds_read_b128 v[8:11], v169 offset:16
	ds_read_b128 v[12:15], v169 offset:32
	ds_read_b128 v[16:19], v169 offset:48
	ds_read_b128 v[20:23], v169 offset:8208
	s_waitcnt lgkmcnt(4)
	v_pk_add_f32 v[44:45], v[6:7], v[2:3]
	v_pk_add_f32 v[46:47], v[4:5], v[0:1]
	ds_read_b128 v[24:27], v169 offset:16384
	ds_read_b128 v[28:31], v169 offset:24576
	global_load_dwordx4 v[4:7], v[40:41], off offset:16 nt
	global_load_dwordx4 v[32:35], v[40:41], off nt
	global_load_dwordx4 v[0:3], v[150:151], off offset:16 nt
	global_load_dwordx4 v[36:39], v[150:151], off nt
	ds_read_b128 v[40:43], v169 offset:16400
	s_waitcnt lgkmcnt(3)
	v_pk_add_f32 v[10:11], v[10:11], v[22:23]
	s_waitcnt lgkmcnt(2)
	v_pk_add_f32 v[48:49], v[44:45], v[26:27]
	v_pk_add_f32 v[50:51], v[46:47], v[24:25]
	ds_read_b128 v[24:27], v169 offset:32768
	ds_read_b128 v[44:47], v169 offset:24592
	s_waitcnt lgkmcnt(3)
	v_pk_add_f32 v[52:53], v[48:49], v[30:31]
	v_pk_add_f32 v[54:55], v[50:51], v[28:29]
	ds_read_b128 v[28:31], v169 offset:40960
	ds_read_b128 v[48:51], v169 offset:32784
	s_waitcnt lgkmcnt(3)
	v_pk_add_f32 v[56:57], v[52:53], v[26:27]
	v_pk_add_f32 v[58:59], v[54:55], v[24:25]
	ds_read_b128 v[24:27], v169 offset:49152
	ds_read_b128 v[52:55], v169 offset:40976
	s_waitcnt lgkmcnt(3)
	v_pk_add_f32 v[60:61], v[56:57], v[30:31]
	v_pk_add_f32 v[62:63], v[58:59], v[28:29]
	ds_read_b128 v[28:31], v169 offset:57344
	ds_read_b128 v[56:59], v169 offset:49168
	v_pk_add_f32 v[8:9], v[8:9], v[20:21]
	v_pk_add_f32 v[10:11], v[10:11], v[42:43]
	v_pk_add_f32 v[8:9], v[8:9], v[40:41]
	s_waitcnt lgkmcnt(3)
	v_pk_add_f32 v[60:61], v[60:61], v[26:27]
	v_pk_add_f32 v[62:63], v[62:63], v[24:25]
	ds_read_b128 v[24:27], v169 offset:57360
	v_pk_add_f32 v[10:11], v[10:11], v[46:47]
	v_pk_add_f32 v[8:9], v[8:9], v[44:45]
	v_pk_add_f32 v[10:11], v[10:11], v[50:51]
	v_pk_add_f32 v[8:9], v[8:9], v[48:49]
	s_waitcnt lgkmcnt(3)
	v_pk_add_f32 v[10:11], v[10:11], v[54:55]
	v_pk_add_f32 v[8:9], v[8:9], v[52:53]
	s_waitcnt lgkmcnt(1)
	v_pk_add_f32 v[20:21], v[10:11], v[58:59]
	v_pk_add_f32 v[22:23], v[8:9], v[56:57]
	ds_read_b128 v[8:11], v169 offset:8224
	s_waitcnt lgkmcnt(1)
	v_pk_add_f32 v[52:53], v[20:21], v[26:27]
	v_pk_add_f32 v[54:55], v[22:23], v[24:25]
	ds_read_b128 v[20:23], v169 offset:16416
	ds_read_b128 v[24:27], v169 offset:8240
	v_pk_add_f32 v[60:61], v[60:61], v[30:31]
	v_pk_add_f32 v[62:63], v[62:63], v[28:29]
	s_waitcnt lgkmcnt(2)
	v_pk_add_f32 v[28:29], v[14:15], v[10:11]
	v_pk_add_f32 v[30:31], v[12:13], v[8:9]
	ds_read_b128 v[8:11], v169 offset:24608
	ds_read_b128 v[12:15], v169 offset:16432
	s_waitcnt lgkmcnt(3)
	v_pk_add_f32 v[40:41], v[28:29], v[22:23]
	v_pk_add_f32 v[42:43], v[30:31], v[20:21]
	ds_read_b128 v[20:23], v169 offset:32800
	ds_read_b128 v[28:31], v169 offset:24624
	s_waitcnt lgkmcnt(3)
	v_pk_add_f32 v[44:45], v[40:41], v[10:11]
	v_pk_add_f32 v[46:47], v[42:43], v[8:9]
	ds_read_b128 v[8:11], v169 offset:40992
	ds_read_b128 v[40:43], v169 offset:32816
	s_waitcnt lgkmcnt(3)
	v_pk_add_f32 v[48:49], v[44:45], v[22:23]
	v_pk_add_f32 v[50:51], v[46:47], v[20:21]
	ds_read_b128 v[20:23], v169 offset:49184
	ds_read_b128 v[44:47], v169 offset:41008
	s_waitcnt lgkmcnt(3)
	v_pk_add_f32 v[56:57], v[48:49], v[10:11]
	v_pk_add_f32 v[58:59], v[50:51], v[8:9]
	ds_read_b128 v[8:11], v169 offset:57376
	ds_read_b128 v[48:51], v169 offset:49200
	v_pk_add_f32 v[16:17], v[16:17], v[24:25]
	s_waitcnt lgkmcnt(3)
	v_pk_add_f32 v[56:57], v[56:57], v[22:23]
	v_pk_add_f32 v[58:59], v[58:59], v[20:21]
	ds_read_b128 v[20:23], v169 offset:57392
	v_pk_add_f32 v[12:13], v[16:17], v[12:13]
	v_pk_add_f32 v[18:19], v[18:19], v[26:27]
	v_pk_add_f32 v[12:13], v[12:13], v[28:29]
	v_pk_add_f32 v[14:15], v[18:19], v[14:15]
	v_pk_add_f32 v[12:13], v[12:13], v[40:41]
	v_pk_add_f32 v[14:15], v[14:15], v[30:31]
	s_waitcnt lgkmcnt(3)
	v_pk_add_f32 v[12:13], v[12:13], v[44:45]
	v_pk_add_f32 v[14:15], v[14:15], v[42:43]
	s_waitcnt lgkmcnt(1)
	v_pk_add_f32 v[12:13], v[12:13], v[48:49]
	v_pk_add_f32 v[14:15], v[14:15], v[46:47]
	s_waitcnt lgkmcnt(0)
	v_pk_add_f32 v[12:13], v[12:13], v[20:21]
	v_pk_add_f32 v[14:15], v[14:15], v[50:51]
	v_pk_add_f32 v[10:11], v[56:57], v[10:11]
	v_pk_add_f32 v[14:15], v[14:15], v[22:23]
	v_pk_add_f32 v[8:9], v[58:59], v[8:9]
	s_cmp_lt_i32 s96, 0
	v_readlane_b32 s36, v251, 3
	s_cselect_b32 s11, s11, 0
	s_cselect_b32 s10, s10, s96
	v_readlane_b32 s42, v251, 9
	v_readlane_b32 s43, v251, 10
	v_readlane_b32 s44, v251, 11
	v_readlane_b32 s45, v251, 12
	s_waitcnt vmcnt(2)
	v_lshlrev_b32_e32 v16, 16, v32
	v_and_b32_e32 v17, 0xffff0000, v32
	s_waitcnt vmcnt(0)
	v_lshlrev_b32_e32 v18, 16, v36
	v_and_b32_e32 v19, 0xffff0000, v36
	v_pk_fma_f32 v[18:19], v[18:19], s[8:9], v[62:63] op_sel_hi:[1,0,1]
	v_lshlrev_b32_e32 v20, 16, v37
	v_and_b32_e32 v21, 0xffff0000, v37
	v_pk_add_f32 v[16:17], v[18:19], v[16:17]
	v_lshlrev_b32_e32 v18, 16, v33
	v_and_b32_e32 v19, 0xffff0000, v33
	v_pk_fma_f32 v[20:21], v[20:21], s[8:9], v[60:61] op_sel_hi:[1,0,1]
	v_lshlrev_b32_e32 v24, 16, v38
	v_pk_add_f32 v[18:19], v[20:21], v[18:19]
	v_mov_b32_e32 v20, v16
	v_mov_b32_e32 v21, v19
	v_pk_mov_b32 v[22:23], v[16:17], v[18:19] op_sel:[1,0]
	v_and_b32_e32 v25, 0xffff0000, v38
	v_pk_add_f32 v[20:21], v[20:21], v[22:23]
	v_lshlrev_b32_e32 v22, 16, v34
	v_and_b32_e32 v23, 0xffff0000, v34
	v_pk_fma_f32 v[24:25], v[24:25], s[8:9], v[54:55] op_sel_hi:[1,0,1]
	v_lshlrev_b32_e32 v26, 16, v39
	v_and_b32_e32 v27, 0xffff0000, v39
	v_pk_add_f32 v[22:23], v[24:25], v[22:23]
	v_lshlrev_b32_e32 v24, 16, v35
	v_and_b32_e32 v25, 0xffff0000, v35
	v_pk_fma_f32 v[26:27], v[26:27], s[8:9], v[52:53] op_sel_hi:[1,0,1]
	v_lshlrev_b32_e32 v30, 16, v0
	v_pk_add_f32 v[24:25], v[26:27], v[24:25]
	v_mov_b32_e32 v26, v22
	v_mov_b32_e32 v27, v25
	v_pk_mov_b32 v[28:29], v[22:23], v[24:25] op_sel:[1,0]
	v_and_b32_e32 v31, 0xffff0000, v0
	v_lshlrev_b32_e32 v0, 16, v1
	v_and_b32_e32 v1, 0xffff0000, v1
	v_pk_add_f32 v[26:27], v[26:27], v[28:29]
	v_lshlrev_b32_e32 v28, 16, v4
	v_and_b32_e32 v29, 0xffff0000, v4
	v_pk_fma_f32 v[8:9], v[30:31], s[8:9], v[8:9] op_sel_hi:[1,0,1]
	v_lshlrev_b32_e32 v4, 16, v5
	v_and_b32_e32 v5, 0xffff0000, v5
	v_pk_fma_f32 v[0:1], v[0:1], s[8:9], v[10:11] op_sel_hi:[1,0,1]
	v_lshlrev_b32_e32 v30, 16, v2
	v_and_b32_e32 v31, 0xffff0000, v2
	v_pk_add_f32 v[10:11], v[0:1], v[4:5]
	v_lshlrev_b32_e32 v4, 16, v6
	v_and_b32_e32 v5, 0xffff0000, v6
	v_pk_fma_f32 v[12:13], v[30:31], s[8:9], v[12:13] op_sel_hi:[1,0,1]
	v_lshlrev_b32_e32 v2, 16, v3
	v_and_b32_e32 v3, 0xffff0000, v3
	v_pk_add_f32 v[8:9], v[8:9], v[28:29]
	v_pk_add_f32 v[12:13], v[12:13], v[4:5]
	v_lshlrev_b32_e32 v4, 16, v7
	v_and_b32_e32 v5, 0xffff0000, v7
	v_pk_fma_f32 v[2:3], v[2:3], s[8:9], v[14:15] op_sel_hi:[1,0,1]
	v_add_f32_e32 v20, v20, v21
	v_pk_add_f32 v[26:27], v[26:27], v[26:27] op_sel:[0,1] op_sel_hi:[1,0]
	v_pk_add_f32 v[28:29], v[8:9], v[8:9] op_sel:[0,1] op_sel_hi:[1,0]
	v_pk_add_f32 v[0:1], v[10:11], v[10:11] op_sel:[1,0] op_sel_hi:[0,1]
	v_pk_add_f32 v[14:15], v[2:3], v[4:5]
	v_add_f32_e32 v20, 0, v20
	v_mov_b32_e32 v21, v12
	v_mov_b32_e32 v27, v13
	v_mov_b32_e32 v29, v15
	v_mov_b32_e32 v1, v14
	v_pk_add_f32 v[2:3], v[20:21], v[26:27]
	v_pk_add_f32 v[0:1], v[28:29], v[0:1]
	s_cselect_b32 s12, s43, s45
	v_pk_add_f32 v[0:1], v[2:3], v[0:1]
	s_cselect_b32 s13, s42, s44
	v_add_f32_e32 v0, v0, v1
	ds_bpermute_b32 v1, v181, v0
	s_lshl_b64 s[10:11], s[10:11], 12
	s_add_u32 s10, s13, s10
	s_addc_u32 s11, s12, s11
	v_readlane_b32 s37, v251, 4
	s_waitcnt lgkmcnt(0)
	v_add_f32_e32 v0, v0, v1
	ds_bpermute_b32 v1, v180, v0
	v_readlane_b32 s38, v251, 5
	v_readlane_b32 s39, v251, 6
	v_readlane_b32 s40, v251, 7
	v_readlane_b32 s41, v251, 8
	s_waitcnt lgkmcnt(0)
	v_add_f32_e32 v0, v0, v1
	ds_bpermute_b32 v1, v179, v0
	v_readlane_b32 s46, v251, 13
	v_readlane_b32 s47, v251, 14
	v_readlane_b32 s48, v251, 15
	v_readlane_b32 s49, v251, 16
	s_waitcnt lgkmcnt(0)
	v_add_f32_e32 v0, v0, v1
	ds_bpermute_b32 v1, v178, v0
	v_readlane_b32 s50, v251, 17
	v_readlane_b32 s51, v251, 18
	s_waitcnt lgkmcnt(0)
	v_add_f32_e32 v0, v0, v1
	ds_bpermute_b32 v1, v177, v0
	s_waitcnt lgkmcnt(0)
	v_add_f32_e32 v20, v0, v1
	global_load_dwordx4 v[0:3], v[146:147], off
	global_load_dwordx4 v[4:7], v[148:149], off
	ds_bpermute_b32 v21, v176, v20
	s_waitcnt lgkmcnt(0)
	v_add_f32_e32 v20, v20, v21
	v_mul_f32_e32 v20, 0x3a800000, v20
	v_pk_add_f32 v[16:17], v[16:17], v[20:21] op_sel_hi:[1,0] neg_lo:[0,1] neg_hi:[0,1]
	v_pk_add_f32 v[18:19], v[18:19], v[20:21] op_sel_hi:[1,0] neg_lo:[0,1] neg_hi:[0,1]
	v_pk_mul_f32 v[26:27], v[16:17], v[16:17]
	v_pk_mul_f32 v[28:29], v[18:19], v[18:19]
	v_add_f32_e32 v26, v26, v27
	v_pk_add_f32 v[22:23], v[22:23], v[20:21] op_sel_hi:[1,0] neg_lo:[0,1] neg_hi:[0,1]
	v_add_f32_e32 v26, v28, v26
	v_pk_mul_f32 v[30:31], v[22:23], v[22:23]
	v_add_f32_e32 v26, v29, v26
	v_pk_add_f32 v[24:25], v[24:25], v[20:21] op_sel_hi:[1,0] neg_lo:[0,1] neg_hi:[0,1]
	v_add_f32_e32 v26, v30, v26
	v_pk_mul_f32 v[32:33], v[24:25], v[24:25]
	v_add_f32_e32 v26, v31, v26
	v_pk_add_f32 v[8:9], v[8:9], v[20:21] op_sel_hi:[1,0] neg_lo:[0,1] neg_hi:[0,1]
	v_add_f32_e32 v26, v32, v26
	v_pk_mul_f32 v[34:35], v[8:9], v[8:9]
	v_add_f32_e32 v26, v33, v26
	v_pk_add_f32 v[10:11], v[10:11], v[20:21] op_sel_hi:[1,0] neg_lo:[0,1] neg_hi:[0,1]
	v_add_f32_e32 v26, v34, v26
	v_pk_mul_f32 v[36:37], v[10:11], v[10:11]
	v_add_f32_e32 v26, v35, v26
	v_pk_add_f32 v[12:13], v[12:13], v[20:21] op_sel_hi:[1,0] neg_lo:[0,1] neg_hi:[0,1]
	v_add_f32_e32 v26, v36, v26
	v_pk_mul_f32 v[38:39], v[12:13], v[12:13]
	v_add_f32_e32 v26, v37, v26
	v_pk_add_f32 v[14:15], v[14:15], v[20:21] op_sel_hi:[1,0] neg_lo:[0,1] neg_hi:[0,1]
	v_add_f32_e32 v26, v38, v26
	v_pk_mul_f32 v[20:21], v[14:15], v[14:15]
	v_add_f32_e32 v26, v39, v26
	v_add_f32_e32 v20, v20, v26
	v_add_f32_e32 v20, v21, v20
	ds_bpermute_b32 v21, v181, v20
	s_waitcnt lgkmcnt(0)
	v_add_f32_e32 v20, v20, v21
	ds_bpermute_b32 v21, v180, v20
	s_waitcnt lgkmcnt(0)
	v_add_f32_e32 v20, v20, v21
	ds_bpermute_b32 v21, v179, v20
	s_waitcnt lgkmcnt(0)
	v_add_f32_e32 v20, v20, v21
	ds_bpermute_b32 v21, v178, v20
	s_waitcnt lgkmcnt(0)
	v_add_f32_e32 v20, v20, v21
	ds_bpermute_b32 v21, v177, v20
	s_waitcnt lgkmcnt(0)
	v_add_f32_e32 v20, v20, v21
	ds_bpermute_b32 v21, v176, v20
	s_waitcnt lgkmcnt(0)
	v_add_f32_e32 v20, v20, v21
	v_fmamk_f32 v20, v20, 0x3a800000, v172
	v_mul_f32_e32 v21, 0x4b800000, v20
	v_cmp_gt_f32_e64 s[2:3], s31, v20
	s_nop 1
	v_cndmask_b32_e64 v20, v20, v21, s[2:3]
	v_rsq_f32_e32 v20, v20
	s_nop 0
	v_mul_f32_e32 v21, 0x45800000, v20
	v_cndmask_b32_e64 v20, v20, v21, s[2:3]
	v_pk_mul_f32 v[16:17], v[16:17], v[20:21] op_sel_hi:[1,0]
	v_pk_mul_f32 v[8:9], v[8:9], v[20:21] op_sel_hi:[1,0]
	s_waitcnt vmcnt(0)
	v_pk_fma_f32 v[0:1], v[0:1], v[16:17], v[4:5]
	v_pk_mul_f32 v[4:5], v[18:19], v[20:21] op_sel_hi:[1,0]
	v_pk_mul_f32 v[16:17], v[22:23], v[20:21] op_sel_hi:[1,0]
	v_pk_fma_f32 v[2:3], v[2:3], v[4:5], v[6:7]
	global_store_dwordx4 v171, v[0:3], s[10:11]
	global_load_dwordx4 v[0:3], v[146:147], off offset:16
	s_nop 0
	global_load_dwordx4 v[4:7], v[148:149], off offset:16
	v_pk_mul_f32 v[18:19], v[24:25], v[20:21] op_sel_hi:[1,0]
	v_pk_mul_f32 v[10:11], v[10:11], v[20:21] op_sel_hi:[1,0]
	s_waitcnt vmcnt(0)
	v_pk_fma_f32 v[0:1], v[0:1], v[16:17], v[4:5]
	v_pk_fma_f32 v[2:3], v[2:3], v[18:19], v[6:7]
	global_store_dwordx4 v171, v[0:3], s[10:11] offset:16
	global_load_dwordx4 v[0:3], v[146:147], off offset:32
	s_nop 0
	global_load_dwordx4 v[4:7], v[148:149], off offset:32
	s_waitcnt vmcnt(0)
	v_pk_fma_f32 v[0:1], v[0:1], v[8:9], v[4:5]
	v_pk_fma_f32 v[2:3], v[2:3], v[10:11], v[6:7]
	global_store_dwordx4 v171, v[0:3], s[10:11] offset:32
	global_load_dwordx4 v[0:3], v[146:147], off offset:48
	s_nop 0
	global_load_dwordx4 v[4:7], v[148:149], off offset:48
	v_pk_mul_f32 v[8:9], v[12:13], v[20:21] op_sel_hi:[1,0]
	v_pk_mul_f32 v[10:11], v[14:15], v[20:21] op_sel_hi:[1,0]
	s_waitcnt vmcnt(0)
	v_pk_fma_f32 v[0:1], v[8:9], v[0:1], v[4:5]
	v_pk_fma_f32 v[2:3], v[10:11], v[2:3], v[6:7]
	global_store_dwordx4 v171, v[0:3], s[10:11] offset:48
	s_barrier
	s_branch .LBB0_3660
